# wout_v89 + hg_prep state-delta stores widened (permlane16_swap -> dwordx4) + GDN scan snapshot stores made contiguous with permlane32_swap (record layout unchanged)
# speedup vs baseline: 1.0179x; 1.0179x over previous
.LBB0_905:
	s_andn2_b64 vcc, exec, s[0:1]
	s_cbranch_vccnz .LBB0_931
	v_mov_b32_e32 v185, v181
	s_movk_i32 s0, 0x3c0
	v_ashrrev_i32_e32 v167, 6, v185
	v_lshlrev_b32_e32 v192, 10, v167
	v_lshlrev_b32_e32 v0, 6, v185
	v_and_or_b32 v0, v0, s0, v192
	v_lshrrev_b32_e32 v2, 1, v185
	v_ashrrev_i32_e32 v1, 31, v0
	v_and_b32_e32 v168, 24, v2
	v_lshl_add_u64 v[0:1], v[0:1], 1, s[20:21]
	s_waitcnt vmcnt(16)
	v_lshlrev_b32_e32 v160, 1, v168
	v_mov_b32_e32 v161, 0
	v_and_b32_e32 v166, 63, v185
	v_lshl_add_u64 v[0:1], v[0:1], 0, v[160:161]
	s_mov_b64 s[4:5], 0x11048000
	v_lshl_add_u64 v[176:177], v[0:1], 0, s[4:5]
	v_lshl_or_b32 v0, v166, 4, v192
	v_ashrrev_i32_e32 v1, 31, v0
	v_lshlrev_b64 v[162:163], 1, v[0:1]
	v_and_b32_e32 v206, 31, v166
	v_lshlrev_b32_e32 v206, 5, v206
	v_lshrrev_b32_e32 v207, 5, v166
	v_lshl_or_b32 v206, v207, 4, v206
	v_lshl_add_u32 v206, v192, 1, v206
	v_mov_b32_e32 v207, 0
	s_mov_b32 s1, 0
	v_lshl_add_u64 v[164:165], s[20:21], 0, v[162:163]
	s_mov_b64 s[4:5], 0x13148000
	s_lshl_b32 s0, s2, 19
	v_lshl_add_u64 v[178:179], v[164:165], 0, s[4:5]
	s_lshl_b64 s[4:5], s[0:1], 1
	v_lshl_add_u64 v[8:9], v[176:177], 0, s[4:5]
	v_lshl_add_u64 v[16:17], v[178:179], 0, s[4:5]
	s_or_b32 s4, s0, 0x1000
	s_mov_b32 s5, s1
	s_lshl_b64 s[4:5], s[4:5], 1
	v_lshl_add_u64 v[24:25], v[176:177], 0, s[4:5]
	v_lshl_add_u64 v[32:33], v[178:179], 0, s[4:5]
	s_or_b32 s4, s0, 0x2000
	s_mov_b32 s5, s1
	s_lshl_b64 s[4:5], s[4:5], 1
	v_lshl_add_u64 v[40:41], v[176:177], 0, s[4:5]
	v_lshl_add_u64 v[48:49], v[178:179], 0, s[4:5]
	s_or_b32 s4, s0, 0x3000
	s_mov_b32 s5, s1
	s_lshl_b64 s[4:5], s[4:5], 1
	v_lshl_add_u64 v[56:57], v[176:177], 0, s[4:5]
	v_lshl_add_u64 v[64:65], v[178:179], 0, s[4:5]
	s_or_b32 s4, s0, 0x4000
	s_mov_b32 s5, s1
	s_lshl_b64 s[4:5], s[4:5], 1
	v_lshl_add_u64 v[72:73], v[176:177], 0, s[4:5]
	v_lshl_add_u64 v[80:81], v[178:179], 0, s[4:5]
	s_or_b32 s4, s0, 0x5000
	s_mov_b32 s5, s1
	s_lshl_b64 s[4:5], s[4:5], 1
	v_lshl_add_u64 v[88:89], v[176:177], 0, s[4:5]
	v_lshl_add_u64 v[96:97], v[178:179], 0, s[4:5]
	s_or_b32 s4, s0, 0x6000
	s_mov_b32 s5, s1
	s_lshl_b64 s[4:5], s[4:5], 1
	v_lshl_add_u64 v[104:105], v[176:177], 0, s[4:5]
	v_lshl_add_u64 v[108:109], v[178:179], 0, s[4:5]
	s_or_b32 s4, s0, 0x7000
	s_mov_b32 s5, s1
	s_lshl_b64 s[4:5], s[4:5], 1
	v_lshl_add_u64 v[116:117], v[176:177], 0, s[4:5]
	v_lshl_add_u64 v[124:125], v[178:179], 0, s[4:5]
	s_or_b32 s4, s0, 0x8000
	s_mov_b32 s5, s1
	s_lshl_b64 s[4:5], s[4:5], 1
	v_lshl_add_u64 v[132:133], v[176:177], 0, s[4:5]
	v_lshl_add_u64 v[140:141], v[178:179], 0, s[4:5]
	s_or_b32 s4, s0, 0x9000
	s_mov_b32 s5, s1
	s_lshl_b64 s[4:5], s[4:5], 1
	v_lshl_add_u64 v[148:149], v[176:177], 0, s[4:5]
	v_lshl_add_u64 v[156:157], v[178:179], 0, s[4:5]
	s_barrier
	global_load_dwordx4 v[0:3], v[8:9], off
	global_load_dwordx4 v[4:7], v[8:9], off offset:64
	s_nop 0
	global_load_dwordx4 v[8:11], v[16:17], off offset:16
	global_load_dwordx4 v[12:15], v[16:17], off
	s_nop 0
	global_load_dwordx4 v[16:19], v[24:25], off
	global_load_dwordx4 v[20:23], v[24:25], off offset:64
	s_nop 0
	global_load_dwordx4 v[24:27], v[32:33], off offset:16
	global_load_dwordx4 v[28:31], v[32:33], off
	s_nop 0
	global_load_dwordx4 v[32:35], v[40:41], off
	global_load_dwordx4 v[36:39], v[40:41], off offset:64
	s_nop 0
	global_load_dwordx4 v[40:43], v[48:49], off offset:16
	global_load_dwordx4 v[44:47], v[48:49], off
	s_nop 0
	global_load_dwordx4 v[48:51], v[56:57], off
	global_load_dwordx4 v[52:55], v[56:57], off offset:64
	s_nop 0
	global_load_dwordx4 v[56:59], v[64:65], off offset:16
	global_load_dwordx4 v[60:63], v[64:65], off
	s_nop 0
	global_load_dwordx4 v[64:67], v[72:73], off
	global_load_dwordx4 v[68:71], v[72:73], off offset:64
	s_nop 0
	global_load_dwordx4 v[72:75], v[80:81], off offset:16
	global_load_dwordx4 v[76:79], v[80:81], off
	s_nop 0
	global_load_dwordx4 v[80:83], v[88:89], off
	global_load_dwordx4 v[84:87], v[88:89], off offset:64
	s_nop 0
	global_load_dwordx4 v[88:91], v[96:97], off offset:16
	global_load_dwordx4 v[92:95], v[96:97], off
	s_nop 0
	global_load_dwordx4 v[96:99], v[104:105], off
	global_load_dwordx4 v[100:103], v[104:105], off offset:64
	s_nop 0
	global_load_dwordx4 v[104:107], v[108:109], off offset:16
	s_nop 0
	global_load_dwordx4 v[108:111], v[108:109], off
	s_nop 0
	global_load_dwordx4 v[112:115], v[116:117], off
	s_nop 0
	global_load_dwordx4 v[116:119], v[116:117], off offset:64
	s_nop 0
	global_load_dwordx4 v[120:123], v[124:125], off offset:16
	s_nop 0
	global_load_dwordx4 v[124:127], v[124:125], off
	s_nop 0
	global_load_dwordx4 v[128:131], v[132:133], off
	s_nop 0
	global_load_dwordx4 v[132:135], v[132:133], off offset:64
	s_nop 0
	global_load_dwordx4 v[136:139], v[140:141], off offset:16
	s_nop 0
	global_load_dwordx4 v[140:143], v[140:141], off
	s_nop 0
	global_load_dwordx4 v[144:147], v[148:149], off
	s_nop 0
	global_load_dwordx4 v[148:151], v[148:149], off offset:64
	s_nop 0
	global_load_dwordx4 v[152:155], v[156:157], off offset:16
	s_nop 0
	global_load_dwordx4 v[156:159], v[156:157], off
	s_lshl_b32 s6, s2, 7
	s_mov_b64 s[4:5], 0x17348000
	s_mov_b32 s7, s1
	v_lshl_add_u64 v[186:187], s[20:21], 0, v[206:207]
	v_lshl_add_u64 v[186:187], v[186:187], 0, s[4:5]
	s_or_b32 s4, s0, 0x13000
	s_lshl_b32 s10, s2, 20
	s_lshl_b64 s[6:7], s[6:7], 13
	v_and_b32_e32 v184, 15, v185
	v_or_b32_e32 v166, 48, v166
	s_add_u32 s6, s20, s6
	v_mul_u32_u24_e32 v169, 0x48, v184
	v_mul_u32_u24_e32 v166, 0x48, v166
	s_addc_u32 s7, s21, s7
	v_lshl_or_b32 v164, v167, 5, v168
	v_lshlrev_b32_e32 v165, 1, v169
	v_lshlrev_b32_e32 v166, 1, v166
	v_lshl_add_u64 v[188:189], s[6:7], 0, v[206:207]
	v_mov_b32_e32 v162, v161
	v_mov_b32_e32 v163, v161
	v_add_u32_e32 v193, v164, v165
	v_add_u32_e32 v194, v164, v166
	v_add_u32_e32 v195, v165, v160
	v_add_u32_e32 v196, v166, v160
	v_mov_b32_e32 v160, v161
	v_mov_b64_e32 v[174:175], v[162:163]
	v_mov_b64_e32 v[170:171], v[162:163]
	v_mov_b64_e32 v[166:167], v[162:163]
	s_mov_b64 s[6:7], 0
	s_mov_b32 s11, 0x17348000
	s_mov_b32 s12, 0x1734a000
	s_mov_b32 s13, 0x1734c000
	s_mov_b32 s14, 0x1734e000
	s_mov_b32 s15, 0x17350000
	s_mov_b32 s16, 0x17352000
	s_mov_b32 s17, 0x17354000
	s_mov_b32 s29, 0x17356000
	v_mov_b64_e32 v[172:173], v[160:161]
	v_mov_b64_e32 v[168:169], v[160:161]
	v_mov_b64_e32 v[164:165], v[160:161]
	s_mov_b32 s34, 0
	s_branch .LBB0_908

.LBB0_908:
	v_lshl_add_u64 v[190:191], v[188:189], 0, s[6:7]
	v_cvt_pk_bf16_f32 v164, v164, v165
	v_cvt_pk_bf16_f32 v165, v166, v167
	v_cvt_pk_bf16_f32 v167, v170, v171
	v_cvt_pk_bf16_f32 v170, v160, v161
	v_add_co_u32_e32 v160, vcc, s11, v190
	v_cvt_pk_bf16_f32 v166, v168, v169
	v_cvt_pk_bf16_f32 v168, v172, v173
	v_cvt_pk_bf16_f32 v169, v174, v175
	v_cvt_pk_bf16_f32 v171, v162, v163
	v_addc_co_u32_e32 v161, vcc, 0, v191, vcc
	ds_write_b64 v193, v[164:165]
	ds_write_b64 v193, v[166:167] offset:2304
	ds_write_b64 v193, v[168:169] offset:4608
	ds_write_b64 v194, v[170:171]
	s_nop 1
	v_permlane32_swap_b32_e32 v164, v168
	v_permlane32_swap_b32_e32 v165, v169
	v_permlane32_swap_b32_e32 v166, v170
	v_permlane32_swap_b32_e32 v167, v171
	global_store_dwordx4 v[160:161], v[164:167], off
	global_store_dwordx4 v[160:161], v[168:171], off offset:1024
	s_waitcnt lgkmcnt(0)
	s_barrier
	ds_read_b128 v[164:167], v195
	ds_read_b128 v[168:171], v195 offset:64
	s_waitcnt vmcnt(16)
	v_lshlrev_b32_e32 v160, 16, v12
	v_and_b32_e32 v161, 0xffff0000, v12
	v_lshlrev_b32_e32 v162, 16, v13
	v_and_b32_e32 v163, 0xffff0000, v13
	ds_read_b128 v[172:175], v195 offset:2368
	ds_read_b128 v[198:201], v195 offset:4672
	s_waitcnt lgkmcnt(3)
	v_mfma_f32_16x16x32_bf16 v[160:163], v[0:3], v[164:167], v[160:163]
	v_lshlrev_b32_e32 v164, 16, v14
	v_and_b32_e32 v165, 0xffff0000, v14
	v_lshlrev_b32_e32 v166, 16, v15
	s_waitcnt lgkmcnt(2)
	v_mfma_f32_16x16x32_bf16 v[160:163], v[4:7], v[168:171], v[160:163]
	ds_read_b128 v[168:171], v195 offset:2304
	v_and_b32_e32 v167, 0xffff0000, v15
	ds_read_b128 v[202:205], v196 offset:64
	s_cmpk_lt_u32 s34, 0x76
	s_waitcnt lgkmcnt(1)
	v_mfma_f32_16x16x32_bf16 v[164:167], v[0:3], v[168:171], v[164:167]
	v_lshlrev_b32_e32 v168, 16, v8
	v_and_b32_e32 v169, 0xffff0000, v8
	v_lshlrev_b32_e32 v170, 16, v9
	v_mfma_f32_16x16x32_bf16 v[164:167], v[4:7], v[172:175], v[164:167]
	ds_read_b128 v[172:175], v195 offset:4608
	v_and_b32_e32 v171, 0xffff0000, v9
	s_cselect_b64 s[8:9], -1, 0
	s_and_b64 vcc, exec, s[8:9]
	s_waitcnt lgkmcnt(0)
	v_mfma_f32_16x16x32_bf16 v[168:171], v[0:3], v[172:175], v[168:171]
	v_lshlrev_b32_e32 v172, 16, v10
	v_and_b32_e32 v173, 0xffff0000, v10
	v_lshlrev_b32_e32 v174, 16, v11
	v_mfma_f32_16x16x32_bf16 v[168:171], v[4:7], v[198:201], v[168:171]
	ds_read_b128 v[198:201], v196
	v_and_b32_e32 v175, 0xffff0000, v11
	s_waitcnt lgkmcnt(0)
	s_nop 0
	v_mfma_f32_16x16x32_bf16 v[172:175], v[0:3], v[198:201], v[172:175]
	v_mfma_f32_16x16x32_bf16 v[172:175], v[4:7], v[202:205], v[172:175]
	s_cbranch_vccz .LBB0_910
	s_add_i32 s0, s4, 0xffff7000
	s_lshl_b64 s[24:25], s[0:1], 1
	v_lshl_add_u64 v[4:5], v[176:177], 0, s[24:25]
	v_lshl_add_u64 v[12:13], v[178:179], 0, s[24:25]
	global_load_dwordx4 v[0:3], v[4:5], off
	s_nop 0
	global_load_dwordx4 v[4:7], v[4:5], off offset:64
	s_nop 0
	global_load_dwordx4 v[8:11], v[12:13], off offset:16
	s_nop 0
	global_load_dwordx4 v[12:15], v[12:13], off
.LBB0_910:
	v_cvt_pk_bf16_f32 v160, v160, v161
	v_cvt_pk_bf16_f32 v161, v162, v163
	v_cvt_pk_bf16_f32 v162, v164, v165
	v_cvt_pk_bf16_f32 v164, v168, v169
	v_add_co_u32_e32 v168, vcc, s12, v190
	v_cvt_pk_bf16_f32 v163, v166, v167
	v_cvt_pk_bf16_f32 v165, v170, v171
	v_cvt_pk_bf16_f32 v166, v172, v173
	v_cvt_pk_bf16_f32 v167, v174, v175
	v_addc_co_u32_e32 v169, vcc, 0, v191, vcc
	ds_write_b64 v193, v[160:161] offset:9216
	ds_write_b64 v193, v[162:163] offset:11520
	ds_write_b64 v193, v[164:165] offset:13824
	ds_write_b64 v194, v[166:167] offset:9216
	s_nop 1
	v_permlane32_swap_b32_e32 v160, v164
	v_permlane32_swap_b32_e32 v161, v165
	v_permlane32_swap_b32_e32 v162, v166
	v_permlane32_swap_b32_e32 v163, v167
	global_store_dwordx4 v[168:169], v[160:163], off
	global_store_dwordx4 v[168:169], v[164:167], off offset:1024
	s_waitcnt lgkmcnt(0)
	s_barrier
	ds_read_b128 v[164:167], v195 offset:9216
	ds_read_b128 v[168:171], v195 offset:9280
	s_waitcnt vmcnt(16)
	v_lshlrev_b32_e32 v160, 16, v28
	v_and_b32_e32 v161, 0xffff0000, v28
	v_lshlrev_b32_e32 v162, 16, v29
	v_and_b32_e32 v163, 0xffff0000, v29
	ds_read_b128 v[172:175], v195 offset:11584
	ds_read_b128 v[198:201], v195 offset:13888
	s_waitcnt lgkmcnt(3)
	v_mfma_f32_16x16x32_bf16 v[160:163], v[16:19], v[164:167], v[160:163]
	v_lshlrev_b32_e32 v164, 16, v30
	v_and_b32_e32 v165, 0xffff0000, v30
	v_lshlrev_b32_e32 v166, 16, v31
	s_waitcnt lgkmcnt(2)
	v_mfma_f32_16x16x32_bf16 v[160:163], v[20:23], v[168:171], v[160:163]
	ds_read_b128 v[168:171], v195 offset:11520
	v_and_b32_e32 v167, 0xffff0000, v31
	ds_read_b128 v[202:205], v196 offset:9280
	s_andn2_b64 vcc, exec, s[8:9]
	s_waitcnt lgkmcnt(1)
	v_mfma_f32_16x16x32_bf16 v[164:167], v[16:19], v[168:171], v[164:167]
	v_lshlrev_b32_e32 v168, 16, v24
	v_and_b32_e32 v169, 0xffff0000, v24
	v_lshlrev_b32_e32 v170, 16, v25
	v_mfma_f32_16x16x32_bf16 v[164:167], v[20:23], v[172:175], v[164:167]
	ds_read_b128 v[172:175], v195 offset:13824
	v_and_b32_e32 v171, 0xffff0000, v25
	s_waitcnt lgkmcnt(0)
	s_nop 0
	v_mfma_f32_16x16x32_bf16 v[168:171], v[16:19], v[172:175], v[168:171]
	v_lshlrev_b32_e32 v172, 16, v26
	v_and_b32_e32 v173, 0xffff0000, v26
	v_lshlrev_b32_e32 v174, 16, v27
	v_mfma_f32_16x16x32_bf16 v[168:171], v[20:23], v[198:201], v[168:171]
	ds_read_b128 v[198:201], v196 offset:9216
	v_and_b32_e32 v175, 0xffff0000, v27
	s_waitcnt lgkmcnt(0)
	s_nop 0
	v_mfma_f32_16x16x32_bf16 v[172:175], v[16:19], v[198:201], v[172:175]
	v_mfma_f32_16x16x32_bf16 v[172:175], v[20:23], v[202:205], v[172:175]
	s_cbranch_vccnz .LBB0_912
	s_add_i32 s0, s4, 0xffff8000
	s_lshl_b64 s[8:9], s[0:1], 1
	v_lshl_add_u64 v[20:21], v[176:177], 0, s[8:9]
	v_lshl_add_u64 v[28:29], v[178:179], 0, s[8:9]
	global_load_dwordx4 v[16:19], v[20:21], off
	s_nop 0
	global_load_dwordx4 v[20:23], v[20:21], off offset:64
	s_nop 0
	global_load_dwordx4 v[24:27], v[28:29], off offset:16
	s_nop 0
	global_load_dwordx4 v[28:31], v[28:29], off
.LBB0_912:
	v_cvt_pk_bf16_f32 v160, v160, v161
	v_cvt_pk_bf16_f32 v161, v162, v163
	v_cvt_pk_bf16_f32 v162, v164, v165
	v_cvt_pk_bf16_f32 v164, v168, v169
	v_add_co_u32_e32 v168, vcc, s13, v190
	v_cvt_pk_bf16_f32 v163, v166, v167
	v_cvt_pk_bf16_f32 v165, v170, v171
	v_cvt_pk_bf16_f32 v166, v172, v173
	v_cvt_pk_bf16_f32 v167, v174, v175
	v_addc_co_u32_e32 v169, vcc, 0, v191, vcc
	ds_write_b64 v193, v[160:161]
	ds_write_b64 v193, v[162:163] offset:2304
	ds_write_b64 v193, v[164:165] offset:4608
	ds_write_b64 v194, v[166:167]
	s_nop 1
	v_permlane32_swap_b32_e32 v160, v164
	v_permlane32_swap_b32_e32 v161, v165
	v_permlane32_swap_b32_e32 v162, v166
	v_permlane32_swap_b32_e32 v163, v167
	global_store_dwordx4 v[168:169], v[160:163], off
	global_store_dwordx4 v[168:169], v[164:167], off offset:1024
	s_waitcnt lgkmcnt(0)
	s_barrier
	ds_read_b128 v[164:167], v195
	ds_read_b128 v[168:171], v195 offset:64
	s_waitcnt vmcnt(16)
	v_lshlrev_b32_e32 v160, 16, v44
	v_and_b32_e32 v161, 0xffff0000, v44
	v_lshlrev_b32_e32 v162, 16, v45
	v_and_b32_e32 v163, 0xffff0000, v45
	ds_read_b128 v[172:175], v195 offset:2368
	ds_read_b128 v[198:201], v195 offset:4672
	s_waitcnt lgkmcnt(3)
	v_mfma_f32_16x16x32_bf16 v[160:163], v[32:35], v[164:167], v[160:163]
	v_lshlrev_b32_e32 v164, 16, v46
	v_and_b32_e32 v165, 0xffff0000, v46
	v_lshlrev_b32_e32 v166, 16, v47
	s_waitcnt lgkmcnt(2)
	v_mfma_f32_16x16x32_bf16 v[160:163], v[36:39], v[168:171], v[160:163]
	ds_read_b128 v[168:171], v195 offset:2304
	v_and_b32_e32 v167, 0xffff0000, v47
	ds_read_b128 v[202:205], v196 offset:64
	s_cmpk_gt_u32 s34, 0x73
	s_waitcnt lgkmcnt(1)
	v_mfma_f32_16x16x32_bf16 v[164:167], v[32:35], v[168:171], v[164:167]
	v_lshlrev_b32_e32 v168, 16, v40
	v_and_b32_e32 v169, 0xffff0000, v40
	v_lshlrev_b32_e32 v170, 16, v41
	v_mfma_f32_16x16x32_bf16 v[164:167], v[36:39], v[172:175], v[164:167]
	ds_read_b128 v[172:175], v195 offset:4608
	v_and_b32_e32 v171, 0xffff0000, v41
	s_waitcnt lgkmcnt(0)
	s_nop 0
	v_mfma_f32_16x16x32_bf16 v[168:171], v[32:35], v[172:175], v[168:171]
	v_lshlrev_b32_e32 v172, 16, v42
	v_and_b32_e32 v173, 0xffff0000, v42
	v_lshlrev_b32_e32 v174, 16, v43
	v_mfma_f32_16x16x32_bf16 v[168:171], v[36:39], v[198:201], v[168:171]
	ds_read_b128 v[198:201], v196
	v_and_b32_e32 v175, 0xffff0000, v43
	s_waitcnt lgkmcnt(0)
	s_nop 0
	v_mfma_f32_16x16x32_bf16 v[172:175], v[32:35], v[198:201], v[172:175]
	v_mfma_f32_16x16x32_bf16 v[172:175], v[36:39], v[202:205], v[172:175]
	s_cbranch_scc1 .LBB0_914
	s_add_i32 s0, s4, 0xffff9000
	s_lshl_b64 s[8:9], s[0:1], 1
	v_lshl_add_u64 v[36:37], v[176:177], 0, s[8:9]
	v_lshl_add_u64 v[44:45], v[178:179], 0, s[8:9]
	global_load_dwordx4 v[32:35], v[36:37], off
	s_nop 0
	global_load_dwordx4 v[36:39], v[36:37], off offset:64
	s_nop 0
	global_load_dwordx4 v[40:43], v[44:45], off offset:16
	s_nop 0
	global_load_dwordx4 v[44:47], v[44:45], off
.LBB0_914:
	v_cvt_pk_bf16_f32 v160, v160, v161
	v_cvt_pk_bf16_f32 v161, v162, v163
	v_cvt_pk_bf16_f32 v162, v164, v165
	v_cvt_pk_bf16_f32 v164, v168, v169
	v_add_co_u32_e32 v168, vcc, s14, v190
	v_cvt_pk_bf16_f32 v163, v166, v167
	v_cvt_pk_bf16_f32 v165, v170, v171
	v_cvt_pk_bf16_f32 v166, v172, v173
	v_cvt_pk_bf16_f32 v167, v174, v175
	v_addc_co_u32_e32 v169, vcc, 0, v191, vcc
	ds_write_b64 v193, v[160:161] offset:9216
	ds_write_b64 v193, v[162:163] offset:11520
	ds_write_b64 v193, v[164:165] offset:13824
	ds_write_b64 v194, v[166:167] offset:9216
	s_nop 1
	v_permlane32_swap_b32_e32 v160, v164
	v_permlane32_swap_b32_e32 v161, v165
	v_permlane32_swap_b32_e32 v162, v166
	v_permlane32_swap_b32_e32 v163, v167
	global_store_dwordx4 v[168:169], v[160:163], off
	global_store_dwordx4 v[168:169], v[164:167], off offset:1024
	s_waitcnt lgkmcnt(0)
	s_barrier
	ds_read_b128 v[164:167], v195 offset:9216
	ds_read_b128 v[168:171], v195 offset:9280
	s_waitcnt vmcnt(16)
	v_lshlrev_b32_e32 v160, 16, v60
	v_and_b32_e32 v161, 0xffff0000, v60
	v_lshlrev_b32_e32 v162, 16, v61
	v_and_b32_e32 v163, 0xffff0000, v61
	ds_read_b128 v[172:175], v195 offset:11584
	ds_read_b128 v[198:201], v195 offset:13888
	s_waitcnt lgkmcnt(3)
	v_mfma_f32_16x16x32_bf16 v[160:163], v[48:51], v[164:167], v[160:163]
	v_lshlrev_b32_e32 v164, 16, v62
	v_and_b32_e32 v165, 0xffff0000, v62
	v_lshlrev_b32_e32 v166, 16, v63
	s_waitcnt lgkmcnt(2)
	v_mfma_f32_16x16x32_bf16 v[160:163], v[52:55], v[168:171], v[160:163]
	ds_read_b128 v[168:171], v195 offset:11520
	v_and_b32_e32 v167, 0xffff0000, v63
	ds_read_b128 v[202:205], v196 offset:9280
	s_cmpk_gt_u32 s34, 0x72
	s_waitcnt lgkmcnt(1)
	v_mfma_f32_16x16x32_bf16 v[164:167], v[48:51], v[168:171], v[164:167]
	v_lshlrev_b32_e32 v168, 16, v56
	v_and_b32_e32 v169, 0xffff0000, v56
	v_lshlrev_b32_e32 v170, 16, v57
	v_mfma_f32_16x16x32_bf16 v[164:167], v[52:55], v[172:175], v[164:167]
	ds_read_b128 v[172:175], v195 offset:13824
	v_and_b32_e32 v171, 0xffff0000, v57
	s_waitcnt lgkmcnt(0)
	s_nop 0
	v_mfma_f32_16x16x32_bf16 v[168:171], v[48:51], v[172:175], v[168:171]
	v_lshlrev_b32_e32 v172, 16, v58
	v_and_b32_e32 v173, 0xffff0000, v58
	v_lshlrev_b32_e32 v174, 16, v59
	v_mfma_f32_16x16x32_bf16 v[168:171], v[52:55], v[198:201], v[168:171]
	ds_read_b128 v[198:201], v196 offset:9216
	v_and_b32_e32 v175, 0xffff0000, v59
	s_waitcnt lgkmcnt(0)
	s_nop 0
	v_mfma_f32_16x16x32_bf16 v[172:175], v[48:51], v[198:201], v[172:175]
	v_mfma_f32_16x16x32_bf16 v[172:175], v[52:55], v[202:205], v[172:175]
	s_cbranch_scc1 .LBB0_916
	s_add_i32 s0, s4, 0xffffa000
	s_lshl_b64 s[8:9], s[0:1], 1
	v_lshl_add_u64 v[52:53], v[176:177], 0, s[8:9]
	v_lshl_add_u64 v[60:61], v[178:179], 0, s[8:9]
	global_load_dwordx4 v[48:51], v[52:53], off
	s_nop 0
	global_load_dwordx4 v[52:55], v[52:53], off offset:64
	s_nop 0
	global_load_dwordx4 v[56:59], v[60:61], off offset:16
	s_nop 0
	global_load_dwordx4 v[60:63], v[60:61], off
.LBB0_916:
	v_cvt_pk_bf16_f32 v160, v160, v161
	v_cvt_pk_bf16_f32 v161, v162, v163
	v_cvt_pk_bf16_f32 v162, v164, v165
	v_cvt_pk_bf16_f32 v164, v168, v169
	v_add_co_u32_e32 v168, vcc, s15, v190
	v_cvt_pk_bf16_f32 v163, v166, v167
	v_cvt_pk_bf16_f32 v165, v170, v171
	v_cvt_pk_bf16_f32 v166, v172, v173
	v_cvt_pk_bf16_f32 v167, v174, v175
	v_addc_co_u32_e32 v169, vcc, 0, v191, vcc
	ds_write_b64 v193, v[160:161]
	ds_write_b64 v193, v[162:163] offset:2304
	ds_write_b64 v193, v[164:165] offset:4608
	ds_write_b64 v194, v[166:167]
	s_nop 1
	v_permlane32_swap_b32_e32 v160, v164
	v_permlane32_swap_b32_e32 v161, v165
	v_permlane32_swap_b32_e32 v162, v166
	v_permlane32_swap_b32_e32 v163, v167
	global_store_dwordx4 v[168:169], v[160:163], off
	global_store_dwordx4 v[168:169], v[164:167], off offset:1024
	s_waitcnt lgkmcnt(0)
	s_barrier
	ds_read_b128 v[164:167], v195
	ds_read_b128 v[168:171], v195 offset:64
	s_waitcnt vmcnt(16)
	v_lshlrev_b32_e32 v160, 16, v76
	v_and_b32_e32 v161, 0xffff0000, v76
	v_lshlrev_b32_e32 v162, 16, v77
	v_and_b32_e32 v163, 0xffff0000, v77
	ds_read_b128 v[172:175], v195 offset:2368
	ds_read_b128 v[198:201], v195 offset:4672
	s_waitcnt lgkmcnt(3)
	v_mfma_f32_16x16x32_bf16 v[160:163], v[64:67], v[164:167], v[160:163]
	v_lshlrev_b32_e32 v164, 16, v78
	v_and_b32_e32 v165, 0xffff0000, v78
	v_lshlrev_b32_e32 v166, 16, v79
	s_waitcnt lgkmcnt(2)
	v_mfma_f32_16x16x32_bf16 v[160:163], v[68:71], v[168:171], v[160:163]
	ds_read_b128 v[168:171], v195 offset:2304
	v_and_b32_e32 v167, 0xffff0000, v79
	ds_read_b128 v[202:205], v196 offset:64
	s_cmpk_gt_u32 s34, 0x71
	s_waitcnt lgkmcnt(1)
	v_mfma_f32_16x16x32_bf16 v[164:167], v[64:67], v[168:171], v[164:167]
	v_lshlrev_b32_e32 v168, 16, v72
	v_and_b32_e32 v169, 0xffff0000, v72
	v_lshlrev_b32_e32 v170, 16, v73
	v_mfma_f32_16x16x32_bf16 v[164:167], v[68:71], v[172:175], v[164:167]
	ds_read_b128 v[172:175], v195 offset:4608
	v_and_b32_e32 v171, 0xffff0000, v73
	s_waitcnt lgkmcnt(0)
	s_nop 0
	v_mfma_f32_16x16x32_bf16 v[168:171], v[64:67], v[172:175], v[168:171]
	v_lshlrev_b32_e32 v172, 16, v74
	v_and_b32_e32 v173, 0xffff0000, v74
	v_lshlrev_b32_e32 v174, 16, v75
	v_mfma_f32_16x16x32_bf16 v[168:171], v[68:71], v[198:201], v[168:171]
	ds_read_b128 v[198:201], v196
	v_and_b32_e32 v175, 0xffff0000, v75
	s_waitcnt lgkmcnt(0)
	s_nop 0
	v_mfma_f32_16x16x32_bf16 v[172:175], v[64:67], v[198:201], v[172:175]
	v_mfma_f32_16x16x32_bf16 v[172:175], v[68:71], v[202:205], v[172:175]
	s_cbranch_scc1 .LBB0_918
	s_add_i32 s0, s4, 0xffffb000
	s_lshl_b64 s[8:9], s[0:1], 1
	v_lshl_add_u64 v[68:69], v[176:177], 0, s[8:9]
	v_lshl_add_u64 v[76:77], v[178:179], 0, s[8:9]
	global_load_dwordx4 v[64:67], v[68:69], off
	s_nop 0
	global_load_dwordx4 v[68:71], v[68:69], off offset:64
	s_nop 0
	global_load_dwordx4 v[72:75], v[76:77], off offset:16
	s_nop 0
	global_load_dwordx4 v[76:79], v[76:77], off
.LBB0_918:
	v_cvt_pk_bf16_f32 v160, v160, v161
	v_cvt_pk_bf16_f32 v161, v162, v163
	v_cvt_pk_bf16_f32 v162, v164, v165
	v_cvt_pk_bf16_f32 v164, v168, v169
	v_add_co_u32_e32 v168, vcc, s16, v190
	v_cvt_pk_bf16_f32 v163, v166, v167
	v_cvt_pk_bf16_f32 v165, v170, v171
	v_cvt_pk_bf16_f32 v166, v172, v173
	v_cvt_pk_bf16_f32 v167, v174, v175
	v_addc_co_u32_e32 v169, vcc, 0, v191, vcc
	ds_write_b64 v193, v[160:161] offset:9216
	ds_write_b64 v193, v[162:163] offset:11520
	ds_write_b64 v193, v[164:165] offset:13824
	ds_write_b64 v194, v[166:167] offset:9216
	s_nop 1
	v_permlane32_swap_b32_e32 v160, v164
	v_permlane32_swap_b32_e32 v161, v165
	v_permlane32_swap_b32_e32 v162, v166
	v_permlane32_swap_b32_e32 v163, v167
	global_store_dwordx4 v[168:169], v[160:163], off
	global_store_dwordx4 v[168:169], v[164:167], off offset:1024
	s_waitcnt lgkmcnt(0)
	s_barrier
	ds_read_b128 v[164:167], v195 offset:9216
	ds_read_b128 v[168:171], v195 offset:9280
	s_waitcnt vmcnt(16)
	v_lshlrev_b32_e32 v160, 16, v92
	v_and_b32_e32 v161, 0xffff0000, v92
	v_lshlrev_b32_e32 v162, 16, v93
	v_and_b32_e32 v163, 0xffff0000, v93
	ds_read_b128 v[172:175], v195 offset:11584
	ds_read_b128 v[198:201], v195 offset:13888
	s_waitcnt lgkmcnt(3)
	v_mfma_f32_16x16x32_bf16 v[160:163], v[80:83], v[164:167], v[160:163]
	v_lshlrev_b32_e32 v164, 16, v94
	v_and_b32_e32 v165, 0xffff0000, v94
	v_lshlrev_b32_e32 v166, 16, v95
	s_waitcnt lgkmcnt(2)
	v_mfma_f32_16x16x32_bf16 v[160:163], v[84:87], v[168:171], v[160:163]
	ds_read_b128 v[168:171], v195 offset:11520
	v_and_b32_e32 v167, 0xffff0000, v95
	ds_read_b128 v[202:205], v196 offset:9280
	s_cmpk_gt_u32 s34, 0x70
	s_waitcnt lgkmcnt(1)
	v_mfma_f32_16x16x32_bf16 v[164:167], v[80:83], v[168:171], v[164:167]
	v_lshlrev_b32_e32 v168, 16, v88
	v_and_b32_e32 v169, 0xffff0000, v88
	v_lshlrev_b32_e32 v170, 16, v89
	v_mfma_f32_16x16x32_bf16 v[164:167], v[84:87], v[172:175], v[164:167]
	ds_read_b128 v[172:175], v195 offset:13824
	v_and_b32_e32 v171, 0xffff0000, v89
	s_waitcnt lgkmcnt(0)
	s_nop 0
	v_mfma_f32_16x16x32_bf16 v[168:171], v[80:83], v[172:175], v[168:171]
	v_lshlrev_b32_e32 v172, 16, v90
	v_and_b32_e32 v173, 0xffff0000, v90
	v_lshlrev_b32_e32 v174, 16, v91
	v_mfma_f32_16x16x32_bf16 v[168:171], v[84:87], v[198:201], v[168:171]
	ds_read_b128 v[198:201], v196 offset:9216
	v_and_b32_e32 v175, 0xffff0000, v91
	s_waitcnt lgkmcnt(0)
	s_nop 0
	v_mfma_f32_16x16x32_bf16 v[172:175], v[80:83], v[198:201], v[172:175]
	v_mfma_f32_16x16x32_bf16 v[172:175], v[84:87], v[202:205], v[172:175]
	s_cbranch_scc1 .LBB0_920
	s_add_i32 s0, s4, 0xffffc000
	s_lshl_b64 s[8:9], s[0:1], 1
	v_lshl_add_u64 v[84:85], v[176:177], 0, s[8:9]
	v_lshl_add_u64 v[92:93], v[178:179], 0, s[8:9]
	global_load_dwordx4 v[80:83], v[84:85], off
	s_nop 0
	global_load_dwordx4 v[84:87], v[84:85], off offset:64
	s_nop 0
	global_load_dwordx4 v[88:91], v[92:93], off offset:16
	s_nop 0
	global_load_dwordx4 v[92:95], v[92:93], off
.LBB0_920:
	v_cvt_pk_bf16_f32 v160, v160, v161
	v_cvt_pk_bf16_f32 v161, v162, v163
	v_cvt_pk_bf16_f32 v162, v164, v165
	v_cvt_pk_bf16_f32 v164, v168, v169
	v_add_co_u32_e32 v168, vcc, s17, v190
	v_cvt_pk_bf16_f32 v163, v166, v167
	v_cvt_pk_bf16_f32 v165, v170, v171
	v_cvt_pk_bf16_f32 v166, v172, v173
	v_cvt_pk_bf16_f32 v167, v174, v175
	v_addc_co_u32_e32 v169, vcc, 0, v191, vcc
	ds_write_b64 v193, v[160:161]
	ds_write_b64 v193, v[162:163] offset:2304
	ds_write_b64 v193, v[164:165] offset:4608
	ds_write_b64 v194, v[166:167]
	s_nop 1
	v_permlane32_swap_b32_e32 v160, v164
	v_permlane32_swap_b32_e32 v161, v165
	v_permlane32_swap_b32_e32 v162, v166
	v_permlane32_swap_b32_e32 v163, v167
	global_store_dwordx4 v[168:169], v[160:163], off
	global_store_dwordx4 v[168:169], v[164:167], off offset:1024
	s_waitcnt lgkmcnt(0)
	s_barrier
	ds_read_b128 v[164:167], v195
	ds_read_b128 v[168:171], v195 offset:64
	s_waitcnt vmcnt(16)
	v_lshlrev_b32_e32 v160, 16, v108
	v_and_b32_e32 v161, 0xffff0000, v108
	v_lshlrev_b32_e32 v162, 16, v109
	v_and_b32_e32 v163, 0xffff0000, v109
	ds_read_b128 v[172:175], v195 offset:2368
	ds_read_b128 v[198:201], v195 offset:4672
	s_waitcnt lgkmcnt(3)
	v_mfma_f32_16x16x32_bf16 v[160:163], v[96:99], v[164:167], v[160:163]
	v_lshlrev_b32_e32 v164, 16, v110
	v_and_b32_e32 v165, 0xffff0000, v110
	v_lshlrev_b32_e32 v166, 16, v111
	s_waitcnt lgkmcnt(2)
	v_mfma_f32_16x16x32_bf16 v[160:163], v[100:103], v[168:171], v[160:163]
	ds_read_b128 v[168:171], v195 offset:2304
	v_and_b32_e32 v167, 0xffff0000, v111
	ds_read_b128 v[202:205], v196 offset:64
	s_cmpk_gt_u32 s34, 0x6f
	s_waitcnt lgkmcnt(1)
	v_mfma_f32_16x16x32_bf16 v[164:167], v[96:99], v[168:171], v[164:167]
	v_lshlrev_b32_e32 v168, 16, v104
	v_and_b32_e32 v169, 0xffff0000, v104
	v_lshlrev_b32_e32 v170, 16, v105
	v_mfma_f32_16x16x32_bf16 v[164:167], v[100:103], v[172:175], v[164:167]
	ds_read_b128 v[172:175], v195 offset:4608
	v_and_b32_e32 v171, 0xffff0000, v105
	s_waitcnt lgkmcnt(0)
	s_nop 0
	v_mfma_f32_16x16x32_bf16 v[168:171], v[96:99], v[172:175], v[168:171]
	v_lshlrev_b32_e32 v172, 16, v106
	v_and_b32_e32 v173, 0xffff0000, v106
	v_lshlrev_b32_e32 v174, 16, v107
	v_mfma_f32_16x16x32_bf16 v[168:171], v[100:103], v[198:201], v[168:171]
	ds_read_b128 v[198:201], v196
	v_and_b32_e32 v175, 0xffff0000, v107
	s_waitcnt lgkmcnt(0)
	s_nop 0
	v_mfma_f32_16x16x32_bf16 v[172:175], v[96:99], v[198:201], v[172:175]
	v_mfma_f32_16x16x32_bf16 v[172:175], v[100:103], v[202:205], v[172:175]
	s_cbranch_scc1 .LBB0_922
	s_add_i32 s0, s4, 0xffffd000
	s_lshl_b64 s[8:9], s[0:1], 1
	v_lshl_add_u64 v[100:101], v[176:177], 0, s[8:9]
	v_lshl_add_u64 v[108:109], v[178:179], 0, s[8:9]
	global_load_dwordx4 v[96:99], v[100:101], off
	s_nop 0
	global_load_dwordx4 v[100:103], v[100:101], off offset:64
	s_nop 0
	global_load_dwordx4 v[104:107], v[108:109], off offset:16
	s_nop 0
	global_load_dwordx4 v[108:111], v[108:109], off
.LBB0_922:
	v_cvt_pk_bf16_f32 v160, v160, v161
	v_cvt_pk_bf16_f32 v161, v162, v163
	v_cvt_pk_bf16_f32 v162, v164, v165
	v_cvt_pk_bf16_f32 v164, v168, v169
	v_add_co_u32_e32 v168, vcc, s29, v190
	v_cvt_pk_bf16_f32 v163, v166, v167
	v_cvt_pk_bf16_f32 v165, v170, v171
	v_cvt_pk_bf16_f32 v166, v172, v173
	v_cvt_pk_bf16_f32 v167, v174, v175
	v_addc_co_u32_e32 v169, vcc, 0, v191, vcc
	ds_write_b64 v193, v[160:161] offset:9216
	ds_write_b64 v193, v[162:163] offset:11520
	ds_write_b64 v193, v[164:165] offset:13824
	ds_write_b64 v194, v[166:167] offset:9216
	s_nop 1
	v_permlane32_swap_b32_e32 v160, v164
	v_permlane32_swap_b32_e32 v161, v165
	v_permlane32_swap_b32_e32 v162, v166
	v_permlane32_swap_b32_e32 v163, v167
	global_store_dwordx4 v[168:169], v[160:163], off
	global_store_dwordx4 v[168:169], v[164:167], off offset:1024
	s_waitcnt lgkmcnt(0)
	s_barrier
	ds_read_b128 v[164:167], v195 offset:9216
	ds_read_b128 v[168:171], v195 offset:9280
	s_waitcnt vmcnt(16)
	v_lshlrev_b32_e32 v160, 16, v124
	v_and_b32_e32 v161, 0xffff0000, v124
	v_lshlrev_b32_e32 v162, 16, v125
	v_and_b32_e32 v163, 0xffff0000, v125
	ds_read_b128 v[172:175], v195 offset:11584
	ds_read_b128 v[198:201], v195 offset:13888
	s_waitcnt lgkmcnt(3)
	v_mfma_f32_16x16x32_bf16 v[160:163], v[112:115], v[164:167], v[160:163]
	ds_read_b128 v[202:205], v196 offset:9280
	s_cmpk_gt_u32 s34, 0x6e
	s_waitcnt lgkmcnt(3)
	v_mfma_f32_16x16x32_bf16 v[164:167], v[116:119], v[168:171], v[160:163]
	ds_read_b128 v[168:171], v195 offset:11520
	s_nop 2
	v_lshlrev_b32_e32 v160, 16, v126
	v_and_b32_e32 v161, 0xffff0000, v126
	v_lshlrev_b32_e32 v162, 16, v127
	v_and_b32_e32 v163, 0xffff0000, v127
	s_waitcnt lgkmcnt(0)
	s_nop 0
	v_mfma_f32_16x16x32_bf16 v[160:163], v[112:115], v[168:171], v[160:163]
	v_mfma_f32_16x16x32_bf16 v[168:171], v[116:119], v[172:175], v[160:163]
	ds_read_b128 v[172:175], v195 offset:13824
	s_nop 5
	v_lshlrev_b32_e32 v160, 16, v120
	v_and_b32_e32 v161, 0xffff0000, v120
	v_lshlrev_b32_e32 v162, 16, v121
	v_and_b32_e32 v163, 0xffff0000, v121
	s_waitcnt lgkmcnt(0)
	s_nop 0
	v_mfma_f32_16x16x32_bf16 v[160:163], v[112:115], v[172:175], v[160:163]
	v_mfma_f32_16x16x32_bf16 v[172:175], v[116:119], v[198:201], v[160:163]
	ds_read_b128 v[198:201], v196 offset:9216
	s_nop 5
	v_lshlrev_b32_e32 v160, 16, v122
	v_and_b32_e32 v161, 0xffff0000, v122
	v_lshlrev_b32_e32 v162, 16, v123
	v_and_b32_e32 v163, 0xffff0000, v123
	s_waitcnt lgkmcnt(0)
	s_nop 0
	v_mfma_f32_16x16x32_bf16 v[160:163], v[112:115], v[198:201], v[160:163]
	v_mfma_f32_16x16x32_bf16 v[160:163], v[116:119], v[202:205], v[160:163]
	s_cbranch_scc1 .LBB0_924
	s_add_i32 s0, s4, 0xffffe000
	s_lshl_b64 s[8:9], s[0:1], 1
	v_lshl_add_u64 v[116:117], v[176:177], 0, s[8:9]
	v_lshl_add_u64 v[124:125], v[178:179], 0, s[8:9]
	global_load_dwordx4 v[112:115], v[116:117], off
	s_nop 0
	global_load_dwordx4 v[116:119], v[116:117], off offset:64
	s_nop 0
	global_load_dwordx4 v[120:123], v[124:125], off offset:16
	s_nop 0
	global_load_dwordx4 v[124:127], v[124:125], off
.LBB0_924:
	s_cmpk_gt_u32 s34, 0x77
	s_cselect_b64 s[8:9], -1, 0
	s_and_b64 vcc, exec, s[8:9]
	s_cbranch_vccnz .LBB0_927
	s_add_i32 s0, s10, s6
	s_add_i32 s0, s0, 0x10000
	v_cvt_pk_bf16_f32 v164, v164, v165
	v_cvt_pk_bf16_f32 v165, v166, v167
	v_cvt_pk_bf16_f32 v166, v168, v169
	v_cvt_pk_bf16_f32 v167, v170, v171
	v_cvt_pk_bf16_f32 v168, v172, v173
	v_cvt_pk_bf16_f32 v169, v174, v175
	v_cvt_pk_bf16_f32 v170, v160, v161
	v_cvt_pk_bf16_f32 v171, v162, v163
	v_lshl_add_u64 v[160:161], v[186:187], 0, s[0:1]
	ds_write_b64 v193, v[164:165]
	ds_write_b64 v193, v[166:167] offset:2304
	ds_write_b64 v193, v[168:169] offset:4608
	ds_write_b64 v194, v[170:171]
	s_nop 1
	v_permlane32_swap_b32_e32 v164, v168
	v_permlane32_swap_b32_e32 v165, v169
	v_permlane32_swap_b32_e32 v166, v170
	v_permlane32_swap_b32_e32 v167, v171
	global_store_dwordx4 v[160:161], v[164:167], off
	global_store_dwordx4 v[160:161], v[168:171], off offset:1024
	s_waitcnt lgkmcnt(0)
	s_barrier
	ds_read_b128 v[164:167], v195
	ds_read_b128 v[168:171], v195 offset:64
	s_waitcnt vmcnt(22)
	v_lshlrev_b32_e32 v160, 16, v140
	v_and_b32_e32 v161, 0xffff0000, v140
	v_lshlrev_b32_e32 v162, 16, v141
	v_and_b32_e32 v163, 0xffff0000, v141
	ds_read_b128 v[172:175], v195 offset:2368
	ds_read_b128 v[198:201], v195 offset:4672
	s_waitcnt lgkmcnt(3)
	v_mfma_f32_16x16x32_bf16 v[160:163], v[128:131], v[164:167], v[160:163]
	s_cmpk_gt_u32 s34, 0x6d
	ds_read_b128 v[202:205], v196 offset:64
	s_waitcnt lgkmcnt(3)
	v_mfma_f32_16x16x32_bf16 v[164:167], v[132:135], v[168:171], v[160:163]
	ds_read_b128 v[168:171], v195 offset:2304
	s_nop 2
	v_lshlrev_b32_e32 v160, 16, v142
	v_and_b32_e32 v161, 0xffff0000, v142
	v_lshlrev_b32_e32 v162, 16, v143
	v_and_b32_e32 v163, 0xffff0000, v143
	s_waitcnt lgkmcnt(0)
	s_nop 0
	v_mfma_f32_16x16x32_bf16 v[160:163], v[128:131], v[168:171], v[160:163]
	v_mfma_f32_16x16x32_bf16 v[168:171], v[132:135], v[172:175], v[160:163]
	ds_read_b128 v[172:175], v195 offset:4608
	s_nop 5
	v_lshlrev_b32_e32 v160, 16, v136
	v_and_b32_e32 v161, 0xffff0000, v136
	v_lshlrev_b32_e32 v162, 16, v137
	v_and_b32_e32 v163, 0xffff0000, v137
	s_waitcnt lgkmcnt(0)
	s_nop 0
	v_mfma_f32_16x16x32_bf16 v[160:163], v[128:131], v[172:175], v[160:163]
	v_mfma_f32_16x16x32_bf16 v[172:175], v[132:135], v[198:201], v[160:163]
	ds_read_b128 v[198:201], v196
	s_nop 5
	v_lshlrev_b32_e32 v160, 16, v138
	v_and_b32_e32 v161, 0xffff0000, v138
	v_lshlrev_b32_e32 v162, 16, v139
	v_and_b32_e32 v163, 0xffff0000, v139
	s_waitcnt lgkmcnt(0)
	s_nop 0
	v_mfma_f32_16x16x32_bf16 v[160:163], v[128:131], v[198:201], v[160:163]
	v_mfma_f32_16x16x32_bf16 v[160:163], v[132:135], v[202:205], v[160:163]
	s_cbranch_scc1 .LBB0_927
	s_add_i32 s0, s4, 0xfffff000
	s_lshl_b64 s[24:25], s[0:1], 1
	v_lshl_add_u64 v[132:133], v[176:177], 0, s[24:25]
	v_lshl_add_u64 v[140:141], v[178:179], 0, s[24:25]
	global_load_dwordx4 v[128:131], v[132:133], off
	s_nop 0
	global_load_dwordx4 v[132:135], v[132:133], off offset:64
	s_nop 0
	global_load_dwordx4 v[136:139], v[140:141], off offset:16
	s_nop 0
	global_load_dwordx4 v[140:143], v[140:141], off
.LBB0_927:
	s_cmpk_gt_u32 s34, 0x76
	s_cbranch_scc1 .LBB0_907
	s_add_i32 s0, s10, s6
	s_add_i32 s0, s0, 0x12000
	v_cvt_pk_bf16_f32 v164, v164, v165
	v_cvt_pk_bf16_f32 v165, v166, v167
	v_cvt_pk_bf16_f32 v166, v168, v169
	v_cvt_pk_bf16_f32 v167, v170, v171
	v_cvt_pk_bf16_f32 v168, v172, v173
	v_cvt_pk_bf16_f32 v169, v174, v175
	v_cvt_pk_bf16_f32 v170, v160, v161
	v_cvt_pk_bf16_f32 v171, v162, v163
	v_lshl_add_u64 v[160:161], v[186:187], 0, s[0:1]
	ds_write_b64 v193, v[164:165] offset:9216
	ds_write_b64 v193, v[166:167] offset:11520
	ds_write_b64 v193, v[168:169] offset:13824
	ds_write_b64 v194, v[170:171] offset:9216
	s_nop 1
	v_permlane32_swap_b32_e32 v164, v168
	v_permlane32_swap_b32_e32 v165, v169
	v_permlane32_swap_b32_e32 v166, v170
	v_permlane32_swap_b32_e32 v167, v171
	global_store_dwordx4 v[160:161], v[164:167], off
	global_store_dwordx4 v[160:161], v[168:171], off offset:1024
	s_waitcnt lgkmcnt(0)
	s_barrier
	ds_read_b128 v[164:167], v195 offset:9216
	ds_read_b128 v[168:171], v195 offset:9280
	s_waitcnt vmcnt(18)
	v_lshlrev_b32_e32 v160, 16, v156
	v_and_b32_e32 v161, 0xffff0000, v156
	v_lshlrev_b32_e32 v162, 16, v157
	v_and_b32_e32 v163, 0xffff0000, v157
	ds_read_b128 v[172:175], v195 offset:11584
	ds_read_b128 v[198:201], v195 offset:13888
	s_waitcnt lgkmcnt(3)
	v_mfma_f32_16x16x32_bf16 v[160:163], v[144:147], v[164:167], v[160:163]
	s_cmpk_gt_u32 s34, 0x6c
	ds_read_b128 v[202:205], v196 offset:9280
	s_waitcnt lgkmcnt(3)
	v_mfma_f32_16x16x32_bf16 v[164:167], v[148:151], v[168:171], v[160:163]
	ds_read_b128 v[168:171], v195 offset:11520
	s_nop 2
	v_lshlrev_b32_e32 v160, 16, v158
	v_and_b32_e32 v161, 0xffff0000, v158
	v_lshlrev_b32_e32 v162, 16, v159
	v_and_b32_e32 v163, 0xffff0000, v159
	s_waitcnt lgkmcnt(0)
	s_nop 0
	v_mfma_f32_16x16x32_bf16 v[160:163], v[144:147], v[168:171], v[160:163]
	v_mfma_f32_16x16x32_bf16 v[168:171], v[148:151], v[172:175], v[160:163]
	ds_read_b128 v[172:175], v195 offset:13824
	s_nop 5
	v_lshlrev_b32_e32 v160, 16, v152
	v_and_b32_e32 v161, 0xffff0000, v152
	v_lshlrev_b32_e32 v162, 16, v153
	v_and_b32_e32 v163, 0xffff0000, v153
	s_waitcnt lgkmcnt(0)
	s_nop 0
	v_mfma_f32_16x16x32_bf16 v[160:163], v[144:147], v[172:175], v[160:163]
	v_mfma_f32_16x16x32_bf16 v[172:175], v[148:151], v[198:201], v[160:163]
	ds_read_b128 v[198:201], v196 offset:9216
	s_nop 5
	v_lshlrev_b32_e32 v160, 16, v154
	v_and_b32_e32 v161, 0xffff0000, v154
	v_lshlrev_b32_e32 v162, 16, v155
	v_and_b32_e32 v163, 0xffff0000, v155
	s_waitcnt lgkmcnt(0)
	s_nop 0
	v_mfma_f32_16x16x32_bf16 v[160:163], v[144:147], v[198:201], v[160:163]
	v_mfma_f32_16x16x32_bf16 v[160:163], v[148:151], v[202:205], v[160:163]
	s_cbranch_scc1 .LBB0_907
	s_mov_b32 s5, s1
	s_lshl_b64 s[24:25], s[4:5], 1
	v_lshl_add_u64 v[148:149], v[176:177], 0, s[24:25]
	v_lshl_add_u64 v[156:157], v[178:179], 0, s[24:25]
	global_load_dwordx4 v[144:147], v[148:149], off
	s_nop 0
	global_load_dwordx4 v[148:151], v[148:149], off offset:64
	s_nop 0
	global_load_dwordx4 v[152:155], v[156:157], off offset:16
	s_nop 0
	global_load_dwordx4 v[156:159], v[156:157], off
	s_branch .LBB0_907
